# P0 work queue: next ticket's atomic issued one item ahead, ticket broadcast through LDS with ds ops (same scheme as the P2.5 queue); dead padding keeps the P4 loop at its address
# speedup vs baseline: 1.0087x; 1.0075x over previous
; DEV void p0_transpose8(const Params& p, int nt2, int kq) {
;   const float* src; int ld, scol; bf16_t* dst;
;   const int nt = nt2 * 2;
;   if (nt < 352) { const int c = nt * 64; src = p.w_in; ld = 22544; scol = c + (c >= 6144 ? 16 : 0); dst = (bf16_t*)(p.ws + OFF_WT_IN) + (size_t)c * 2048; }
;   else if (nt < 416) { const int c = (nt - 352) * 64; src = p.w_mkv; ld = 4096; scol = c; dst = (bf16_t*)(p.ws + OFF_WT_MKV) + (size_t)c * 2048; }
;   else if (nt < 448) { const int c = (nt - 416) * 64; src = p.w_pg; ld = 2048; scol = c; dst = (bf16_t*)(p.ws + OFF_WT_PG) + (size_t)c * 2048; }
;   else if (nt < 480) { const int c = (nt - 448) * 64; src = p.w_ps; ld = 2048; scol = c; dst = (bf16_t*)(p.ws + OFF_WT_PS) + (size_t)c * 2048; }
;   else if (nt < 512) { const int c = (nt - 480) * 64; src = p.w_pm; ld = 2048; scol = c; dst = (bf16_t*)(p.ws + OFF_WT_PM) + (size_t)c * 2048; }
;   else { const int c = (nt - 512) * 64; src = p.w_out; ld = 2048; scol = c; dst = (bf16_t*)(p.ws + OFF_WT_OUT) + (size_t)c * 2048; }
; DEV void phase0(const Params& p) {
;     ...
;     __syncthreads();
;     if (tidx == 0) *slot = first ? (int)blockIdx.x : (int)(gridDim.x + atomicAdd(ctr, 1u));
;     first = false;
;     __syncthreads();
;     const int it = __builtin_amdgcn_readfirstlane(*slot);
;     if (it >= total) break;
;     if (it < 128) p0_chunk(p, it);
;     else if (it < 144) { norm_rows64(p.mem, p.g_mem, (bf16_t*)(p.ws + OFF_MEMH), (it - 128) * 64); }
;     else { const int tt = it - 144; p0_transpose8(p, tt >> 3, tt & 7); }
.LBB0_2120:
	s_or_b64 exec, exec, s[0:1]
	v_mov_b32_e32 v0, 0x20800
	s_waitcnt lgkmcnt(0)
	s_barrier
	ds_read_b32 v0, v0
	s_mov_b64 s[0:1], -1
	s_waitcnt lgkmcnt(0)
	v_readfirstlane_b32 s66, v0
	s_cmpk_gt_i32 s66, 0x90f
	s_cbranch_scc1 .LBB0_2113
	s_cmpk_gt_i32 s66, 0x7f
	s_cbranch_scc0 .LBB0_2146
	s_cmpk_gt_u32 s66, 0x8f
	s_cbranch_scc0 .LBB0_2144
	s_add_i32 s14, s66, 0xffffff70
	s_lshr_b32 s7, s14, 3
	s_cmpk_gt_u32 s14, 0x57f
	s_cbranch_scc0 .LBB0_2129
	s_cmpk_gt_u32 s14, 0x67f
	s_cbranch_scc0 .LBB0_2130
	s_cmpk_gt_u32 s14, 0x6ff
	s_cbranch_scc0 .LBB0_2131
	s_cmpk_gt_u32 s14, 0x77f
	s_cbranch_scc0 .LBB0_2132
	s_lshl_b32 s12, s7, 7
	s_cmpk_gt_u32 s14, 0x7ff
	s_cbranch_scc0 .LBB0_2133
	s_add_i32 s92, s12, 0xffff8000
	s_lshl_b64 s[0:1], s[92:93], 12
	v_readlane_b32 s8, v253, 6
	s_add_u32 s0, s8, s0
	v_readlane_b32 s8, v253, 7
	s_addc_u32 s1, s8, s1
	s_mov_b64 s[8:9], s[58:59]
	s_cbranch_execz .LBB0_2134
	s_branch .LBB0_2135
	s_nop 0
	s_nop 0
	s_nop 0
	s_nop 0
	s_nop 0
	s_nop 0
	s_nop 0
	s_nop 0
	s_nop 0
	s_nop 0
	s_nop 0
	s_nop 0
	s_nop 0
	s_nop 0
	s_nop 0
	s_nop 0
	s_nop 0
	s_nop 0
	s_nop 0
	s_nop 0
	s_nop 0
	s_nop 0
